# speedup vs baseline: 1.0014x; 1.0014x over previous
; template <int DQK, int DV, int MODE> ...
;     ...
;     f32x16 o[DV / 32];
; #pragma unroll
;     for (int d = 0; d < DV / 32; ++d)
; #pragma unroll
;         for (int e = 0; e < 16; ++e) o[d][e] = 0.f;
;     float m = (MODE == 2) ? sink2 : -1e30f, l = (MODE == 2) ? 0.5f : 0.f;
;     const int qa = q0 + wid * 32;
;     const int vlane = (4 * h + ((lane & 15) >> 2)) * VS + (16 * ((lane >> 4) & 1) + 4 * (lane & 3)) * 2;
;     FL_LOAD(0); FL_STORE(0); __syncthreads();
;     if (wid >= 4) __builtin_amdgcn_s_setprio(1);
;     for (int t = 0; t < nt; ++t) {
.LBB0_596:
	v_readfirstlane_b32 s101, v165
	s_lshl_b32 s6, s59, 2
	s_lshl_b32 s0, s58, 8
	s_add_i32 s6, s6, 0
	s_add_i32 s6, s6, 0x16800
	s_lshl_b32 s7, s0, 1
	v_mov_b32_e32 v48, v169
	v_mov_b32_e32 v49, v169
	s_add_u32 s55, s16, s7
	v_mov_b32_e32 v50, v169
	v_mov_b32_e32 v51, v169
	v_mov_b32_e32 v52, v169
	v_mov_b32_e32 v53, v169
	v_mov_b32_e32 v54, v169
	v_mov_b32_e32 v55, v169
	v_mov_b32_e32 v56, v169
	v_mov_b32_e32 v57, v169
	v_mov_b32_e32 v58, v169
	v_mov_b32_e32 v59, v169
	v_mov_b32_e32 v60, v169
	v_mov_b32_e32 v61, v169
	v_mov_b32_e32 v62, v169
	v_mov_b32_e32 v63, v169
	v_mov_b64_e32 v[32:33], v[48:49]
	v_mov_b64_e32 v[16:17], v[48:49]
	v_mov_b64_e32 v[0:1], v[48:49]
	s_addc_u32 s58, s17, 0
	v_lshl_add_u32 v220, v166, 2, s6
	v_lshl_add_u32 v219, v209, 2, s6
	s_add_i32 s54, s9, 3
	s_mov_b32 s59, 0
	v_mov_b32_e32 v223, 0xf149f2ca
	v_mov_b32_e32 v221, 0
	s_mov_b32 s71, 64
	v_mov_b64_e32 v[34:35], v[50:51]
	v_mov_b64_e32 v[36:37], v[52:53]
	v_mov_b64_e32 v[38:39], v[54:55]
	v_mov_b64_e32 v[40:41], v[56:57]
	v_mov_b64_e32 v[42:43], v[58:59]
	v_mov_b64_e32 v[44:45], v[60:61]
	v_mov_b64_e32 v[46:47], v[62:63]
	v_mov_b64_e32 v[18:19], v[50:51]
	v_mov_b64_e32 v[20:21], v[52:53]
	v_mov_b64_e32 v[22:23], v[54:55]
	v_mov_b64_e32 v[24:25], v[56:57]
	v_mov_b64_e32 v[26:27], v[58:59]
	v_mov_b64_e32 v[28:29], v[60:61]
	v_mov_b64_e32 v[30:31], v[62:63]
	v_mov_b64_e32 v[2:3], v[50:51]
	v_mov_b64_e32 v[4:5], v[52:53]
	v_mov_b64_e32 v[6:7], v[54:55]
	v_mov_b64_e32 v[8:9], v[56:57]
	v_mov_b64_e32 v[10:11], v[58:59]
	v_mov_b64_e32 v[12:13], v[60:61]
	v_mov_b64_e32 v[14:15], v[62:63]
.LBB0_597:
	s_cmpk_lt_u32 s101, 0x100
	s_cbranch_scc1 .Lmla_nostag
	s_sleep 8
